# attention: next tile's K-fragment ds_read_b128s issued right after the per-tile barrier, ahead of the global-load issue code (prompt loop, both tiles), on top of v030
# baseline (speedup 1.0000x reference)
; #define LAS __attribute__((address_space(3)))
; DI float fast_exp2(float x) { return __builtin_amdgcn_exp2f(x); }
; #define MFMA16(a, b, c) __builtin_amdgcn_mfma_f32_16x16x32_bf16((a), (b), (c), 0, 0, 0)
; DI void at_qk(f32x4 (&s1)[4], f32x4 (&s2)[4], const LAS unsigned char* buf, const bf16x8 q1, const bf16x8 q2, const f32x4 (&ci)[4], int hh, int fr, int fq) {
; #pragma unroll
;     for (int k4 = 0; k4 < 4; ++k4) { const LAS unsigned char* kr = buf + AT_K + (16 * k4 + fr) * 272 + hh * 128 + fq * 16;
;         s1[k4] = MFMA16(ld8l(kr), q1, ci[k4]); s2[k4] = MFMA16(ld8l(kr + 64), q2, ci[k4]); }
; }
; DI void at_exp(f32x4 (&s1)[4], f32x4 (&s2)[4], float& ps1, float& ps2) {
;     f32x4 a1 = (f32x4){0.f, 0.f, 0.f, 0.f}, a2 = a1;
; #pragma unroll
;     for (int k4 = 0; k4 < 4; ++k4) {
; #pragma unroll
;         for (int j = 0; j < 4; ++j) { s1[k4][j] = fast_exp2(s1[k4][j]); s2[k4][j] = fast_exp2(s2[k4][j]); }
;         a1 = a1 + s1[k4]; a2 = a2 + s2[k4]; }
;     ps1 = (a1[0] + a1[1]) + (a1[2] + a1[3]); ps2 = (a2[0] + a2[1]) + (a2[2] + a2[3]);
; template <int VAR>
; DI void attn_tile(AtState& S, const LAS unsigned char* buf, const bf16x8 q1, const bf16x8 q2, int kt, bool diag, int qpos0, int qpos_l, float slope2, float adv, float decay, int hh, int fr, int fq) {
;     ...
;         asm volatile("; attention: fast tile" ::: "memory");
;         at_qk(s1, s2, buf, q1, q2, S.cinit, hh, fr, fq);
;         S.ref += adv;
;         at_exp(s1, s2, ps1, ps2);
;         if (__any(!(ps1 + ps2 < 0x1p60f))) {
;             asm volatile("; attention: bump" ::: "memory");
;             at_qk(s1, s2, buf, q1, q2, S.cinit, hh, fr, fq);
;             float lm = -1e30f;
; #pragma unroll
;             for (int k4 = 0; k4 < 4; ++k4)
; #pragma unroll
;                 for (int j = 0; j < 4; ++j) lm = fmaxf(lm, fmaxf(s1[k4][j], s2[k4][j]));
;             lm = fmaxf(lm, __shfl_xor(lm, 16)); lm = fmaxf(lm, __shfl_xor(lm, 32));
.LBB0_1376:
	ds_read_b128 v[76:79], v213
	ds_read_b128 v[80:83], v213 offset:64
	ds_read_b128 v[96:99], v213 offset:4352
	ds_read_b128 v[104:107], v213 offset:4416
	ds_read_b128 v[108:111], v213 offset:8704
	ds_read_b128 v[112:115], v213 offset:8768
	ds_read_b128 v[116:119], v213 offset:13056
	ds_read_b128 v[120:123], v213 offset:13120
	s_add_i32 s27, s26, -1
	s_min_i32 s14, s27, s25
	s_ashr_i32 s15, s14, 31
	s_add_i32 s28, s22, s26
	s_lshl_b64 s[14:15], s[14:15], 18
	s_add_u32 s14, s0, s14
	s_addc_u32 s15, s1, s15
	global_load_dwordx4 v[28:31], v144, s[14:15] offset:1024
	global_load_dwordx4 v[32:35], v144, s[14:15] offset:1536
	global_load_dwordx4 v[36:39], v146, s[14:15] offset:1024
	global_load_dwordx4 v[40:43], v146, s[14:15] offset:1536
	s_cmpk_eq_i32 s28, 0x42
	s_cselect_b64 s[16:17], -1, 0
	s_cmp_eq_u32 s26, 3
	s_cselect_b64 s[14:15], -1, 0
	s_or_b64 s[18:19], s[14:15], s[16:17]
	s_andn2_b64 vcc, exec, s[18:19]
	s_mov_b64 s[18:19], -1
	s_cbranch_vccz .LBB0_1381
	s_waitcnt lgkmcnt(7)
	v_mfma_f32_16x16x32_bf16 v[76:79], v[76:79], v[4:7], v[44:47]
	v_add_f32_e32 v215, v205, v214
	s_waitcnt lgkmcnt(6)
	v_mfma_f32_16x16x32_bf16 v[80:83], v[80:83], v[8:11], v[44:47]
	s_waitcnt lgkmcnt(5)
	v_mfma_f32_16x16x32_bf16 v[96:99], v[96:99], v[4:7], v[48:51]
	s_nop 2
	v_exp_f32_e32 v164, v76
	v_exp_f32_e32 v165, v77
	v_exp_f32_e32 v168, v78
	s_waitcnt lgkmcnt(4)
	v_mfma_f32_16x16x32_bf16 v[104:107], v[104:107], v[8:11], v[48:51]
	v_exp_f32_e32 v169, v79
	v_exp_f32_e32 v162, v80
	v_exp_f32_e32 v163, v81
	s_waitcnt lgkmcnt(3)
	v_mfma_f32_16x16x32_bf16 v[108:111], v[108:111], v[4:7], v[52:55]
	v_exp_f32_e32 v166, v82
	v_exp_f32_e32 v167, v83
	v_exp_f32_e32 v172, v96
	s_waitcnt lgkmcnt(2)
	v_mfma_f32_16x16x32_bf16 v[76:79], v[112:115], v[8:11], v[52:55]
	v_exp_f32_e32 v170, v104
	v_exp_f32_e32 v173, v97
	v_exp_f32_e32 v176, v98
	s_waitcnt lgkmcnt(1)
	v_mfma_f32_16x16x32_bf16 v[80:83], v[116:119], v[4:7], v[56:59]
	v_exp_f32_e32 v177, v99
	v_exp_f32_e32 v174, v106
	v_exp_f32_e32 v175, v107
	s_waitcnt lgkmcnt(0)
	v_mfma_f32_16x16x32_bf16 v[112:115], v[120:123], v[8:11], v[56:59]
	v_exp_f32_e32 v171, v105
	v_exp_f32_e32 v180, v108
	v_exp_f32_e32 v178, v76
	v_exp_f32_e32 v181, v109
	v_exp_f32_e32 v179, v77
	v_exp_f32_e32 v184, v110
	v_exp_f32_e32 v185, v111
	v_exp_f32_e32 v182, v78
	v_exp_f32_e32 v183, v79
	v_exp_f32_e32 v188, v80
	v_exp_f32_e32 v186, v112
	v_exp_f32_e32 v189, v81
	v_exp_f32_e32 v192, v82
	v_exp_f32_e32 v193, v83
	v_exp_f32_e32 v190, v114
	v_exp_f32_e32 v191, v115
	v_exp_f32_e32 v187, v113
	v_pk_add_f32 v[96:97], v[168:169], v[176:177]
	v_pk_add_f32 v[98:99], v[164:165], v[172:173]
	v_pk_add_f32 v[104:105], v[166:167], v[174:175]
	v_pk_add_f32 v[106:107], v[162:163], v[170:171]
	v_pk_add_f32 v[76:77], v[98:99], v[180:181]
	v_pk_add_f32 v[78:79], v[96:97], v[184:185]
	v_pk_add_f32 v[96:97], v[106:107], v[178:179]
	v_pk_add_f32 v[98:99], v[104:105], v[182:183]
	v_pk_add_f32 v[78:79], v[78:79], v[192:193]
	v_pk_add_f32 v[76:77], v[76:77], v[188:189]
	v_pk_add_f32 v[80:81], v[98:99], v[190:191]
	v_pk_add_f32 v[82:83], v[96:97], v[186:187]
	v_mov_b32_e32 v97, v76
	v_mov_b32_e32 v96, v82
	v_mov_b32_e32 v76, v83
	v_mov_b32_e32 v82, v80
	v_mov_b32_e32 v83, v78
	v_mov_b32_e32 v78, v81
	v_pk_add_f32 v[76:77], v[96:97], v[76:77]
	v_pk_add_f32 v[78:79], v[82:83], v[78:79]
	s_nop 0
	v_pk_add_f32 v[194:195], v[76:77], v[78:79]
	s_nop 0
	v_add_f32_e32 v3, v195, v194
	v_cmp_ngt_f32_e32 vcc, s65, v3
	s_cbranch_vccz .LBB0_1394
	ds_read_b128 v[76:79], v213
	ds_read_b128 v[80:83], v213 offset:64
	ds_read_b128 v[96:99], v213 offset:4352
	ds_read_b128 v[104:107], v213 offset:4416
	ds_read_b128 v[108:111], v213 offset:8704
	ds_read_b128 v[112:115], v213 offset:8768
	ds_read_b128 v[116:119], v213 offset:13056
	ds_read_b128 v[120:123], v213 offset:13120
	s_waitcnt lgkmcnt(7)
	v_mfma_f32_16x16x32_bf16 v[76:79], v[76:79], v[4:7], v[44:47]
	s_waitcnt lgkmcnt(6)
	v_mfma_f32_16x16x32_bf16 v[80:83], v[80:83], v[8:11], v[44:47]
	s_waitcnt lgkmcnt(5)
	v_mfma_f32_16x16x32_bf16 v[96:99], v[96:99], v[4:7], v[48:51]
	s_waitcnt lgkmcnt(4)
	v_mfma_f32_16x16x32_bf16 v[104:107], v[104:107], v[8:11], v[48:51]
	s_waitcnt lgkmcnt(3)
	v_mfma_f32_16x16x32_bf16 v[108:111], v[108:111], v[4:7], v[52:55]
	s_waitcnt lgkmcnt(2)
	v_mfma_f32_16x16x32_bf16 v[112:115], v[112:115], v[8:11], v[52:55]
	s_waitcnt lgkmcnt(1)
	v_mfma_f32_16x16x32_bf16 v[116:119], v[116:119], v[4:7], v[56:59]
	s_waitcnt lgkmcnt(0)
	v_mfma_f32_16x16x32_bf16 v[120:123], v[120:123], v[8:11], v[56:59]
	v_max3_f32 v3, v76, v80, s60
	v_max3_f32 v3, v3, v77, v81
	v_max3_f32 v3, v3, v78, v82
	v_max3_f32 v3, v3, v79, v83
	v_max3_f32 v3, v3, v96, v104
	v_max3_f32 v3, v3, v97, v105
	v_max3_f32 v3, v3, v98, v106
	v_max3_f32 v3, v3, v99, v107
	v_max3_f32 v3, v3, v108, v112
	v_max3_f32 v3, v3, v109, v113
	v_max3_f32 v3, v3, v110, v114
	v_max3_f32 v3, v3, v111, v115
	v_max3_f32 v3, v3, v116, v120
	v_max3_f32 v3, v3, v117, v121
	v_max3_f32 v3, v3, v118, v122
	v_max3_f32 v3, v3, v119, v123
	v_and_b32_e32 v125, 64, v198
	v_mov_b32_e32 v124, v3
	v_mov_b32_e32 v255, v3
	s_nop 1
	v_permlane16_swap_b32_e32 v124, v255
	s_waitcnt lgkmcnt(0)
	v_max_f32_e32 v3, v124, v255
	v_mov_b32_e32 v124, v3
	v_mov_b32_e32 v255, v3
	s_nop 1
	v_permlane32_swap_b32_e32 v124, v255
	s_waitcnt lgkmcnt(0)
; #define LAS __attribute__((address_space(3)))
; DI float fast_exp2(float x) { return __builtin_amdgcn_exp2f(x); }
; DI u32x2 tr4(const LAS unsigned char* p) { return __builtin_bit_cast(u32x2, __builtin_amdgcn_ds_read_tr16_b64_v4i16((LAS v4i16_t*)p)); }
; DI bf16x8 packp(f32x4 a, f32x4 b) { return __builtin_bit_cast(bf16x8, pack8(a, b)); }
; DI void at_pv(AtState& S, const f32x4 (&s1)[4], const f32x4 (&s2)[4], float alpha, float ps1, float ps2, const LAS unsigned char* buf, int hh, int fq, int tq, int tp) {
;     S.l1 = S.l1 * alpha + ps1; S.l2 = S.l2 * alpha + ps2;
; #pragma unroll
;     for (int dt = 0; dt < 4; ++dt) { S.O1[dt] = S.O1[dt] * alpha; S.O2[dt] = S.O2[dt] * alpha; }
;     bf16x8 p1[2], p2[2];
; #pragma unroll
;     for (int s = 0; s < 2; ++s) { p1[s] = packp(s1[2 * s], s1[2 * s + 1]); p2[s] = packp(s2[2 * s], s2[2 * s + 1]); }
; #pragma unroll
;     for (int dh = 0; dh < 2; ++dh) {
;         bf16x8 vt[2][2];
; #pragma unroll
;         for (int d2 = 0; d2 < 2; ++d2)
; #pragma unroll
;             for (int s = 0; s < 2; ++s) { const int dt = 2 * dh + d2; const LAS unsigned char* vr = buf + AT_V + (32 * s + 4 * fq + tq) * 288 + (hh * 64 + 16 * dt + 4 * tp) * 2; vt[d2][s] = cat44(tr4(vr), tr4(vr + 16 * 288)); }
; template <int VAR>
; DI void attn_tile(AtState& S, const LAS unsigned char* buf, const bf16x8 q1, const bf16x8 q2, int kt, bool diag, int qpos0, int qpos_l, float slope2, float adv, float decay, int hh, int fr, int fq) {
;     ...
;             const float bump = fmaxf(lm, 0.f);
;             const float alpha = decay * fast_exp2(-bump); S.ref += bump;
; #pragma unroll
;             for (int k4 = 0; k4 < 4; ++k4) { s1[k4] = s1[k4] - bump; s2[k4] = s2[k4] - bump; S.cinit[k4] = S.cinit[k4] - bump; }
;             at_exp(s1, s2, ps1, ps2);
;             at_pv(S, s1, s2, alpha, ps1, ps2, buf, hh, fq, tq, tp);
	v_max3_f32 v124, v255, v124, 0
	v_sub_f32_e32 v126, v79, v124
	v_sub_f32_e32 v127, v78, v124
	v_sub_f32_e32 v128, v77, v124
	v_sub_f32_e32 v129, v76, v124
	v_sub_f32_e32 v130, v83, v124
	v_sub_f32_e32 v131, v82, v124
	v_sub_f32_e32 v132, v81, v124
	v_sub_f32_e32 v133, v80, v124
	v_sub_f32_e32 v134, v99, v124
	v_sub_f32_e32 v135, v98, v124
	v_sub_f32_e32 v137, v97, v124
	v_sub_f32_e32 v138, v96, v124
	v_sub_f32_e32 v139, v107, v124
	v_sub_f32_e32 v151, v106, v124
	v_sub_f32_e32 v158, v105, v124
	v_sub_f32_e32 v159, v104, v124
	v_exp_f32_e32 v216, v129
	v_exp_f32_e32 v220, v133
	v_exp_f32_e32 v217, v128
	v_exp_f32_e32 v221, v132
	v_exp_f32_e32 v218, v127
	v_exp_f32_e32 v222, v131
	v_exp_f32_e32 v219, v126
	v_exp_f32_e32 v223, v130
	v_sub_f32_e32 v237, v111, v124
	v_sub_f32_e32 v236, v110, v124
	v_sub_f32_e32 v233, v109, v124
	v_sub_f32_e32 v232, v108, v124
	v_sub_f32_e32 v239, v115, v124
	v_sub_f32_e32 v238, v114, v124
	v_sub_f32_e32 v235, v113, v124
	v_sub_f32_e32 v234, v112, v124
	v_exp_f32_e32 v224, v138
	v_exp_f32_e32 v226, v159
	v_exp_f32_e32 v225, v137
	v_exp_f32_e32 v227, v158
	v_exp_f32_e32 v228, v135
	v_exp_f32_e32 v230, v151
	v_exp_f32_e32 v229, v134
	v_exp_f32_e32 v231, v139
	v_sub_f32_e32 v119, v119, v124
	v_sub_f32_e32 v118, v118, v124
	v_sub_f32_e32 v117, v117, v124
	v_sub_f32_e32 v116, v116, v124
	v_sub_f32_e32 v123, v123, v124
	v_sub_f32_e32 v122, v122, v124
	v_sub_f32_e32 v121, v121, v124
	v_sub_f32_e32 v120, v120, v124
	v_exp_f32_e32 v232, v232
	v_exp_f32_e32 v234, v234
	v_exp_f32_e32 v233, v233
	v_exp_f32_e32 v235, v235
	v_exp_f32_e32 v236, v236
	v_exp_f32_e32 v238, v238
	v_exp_f32_e32 v237, v237
	v_exp_f32_e32 v239, v239
	v_exp_f32_e32 v240, v116
	v_exp_f32_e32 v242, v120
	v_exp_f32_e32 v241, v117
	v_exp_f32_e32 v243, v121
	v_exp_f32_e32 v244, v118
	v_exp_f32_e32 v246, v122
	v_exp_f32_e32 v245, v119
	v_exp_f32_e32 v247, v123
	v_pk_add_f32 v[110:111], v[228:229], v[218:219]
	v_pk_add_f32 v[108:109], v[224:225], v[216:217]
	v_pk_add_f32 v[114:115], v[230:231], v[222:223]
	v_pk_add_f32 v[112:113], v[226:227], v[220:221]
	v_pk_add_f32 v[108:109], v[232:233], v[108:109]
	v_pk_add_f32 v[110:111], v[236:237], v[110:111]
	v_pk_add_f32 v[112:113], v[234:235], v[112:113]
	v_pk_add_f32 v[114:115], v[238:239], v[114:115]
	v_pk_add_f32 v[110:111], v[244:245], v[110:111]
	v_pk_add_f32 v[108:109], v[240:241], v[108:109]
	v_pk_add_f32 v[114:115], v[246:247], v[114:115]
	v_pk_add_f32 v[112:113], v[242:243], v[112:113]
	v_cvt_pk_bf16_f32 v216, v216, v217
	v_cvt_pk_bf16_f32 v217, v218, v219
	v_cvt_pk_bf16_f32 v218, v224, v225
	v_cvt_pk_bf16_f32 v219, v228, v229
	v_cvt_pk_bf16_f32 v220, v220, v221
	v_cvt_pk_bf16_f32 v221, v222, v223
	v_cvt_pk_bf16_f32 v222, v226, v227
	v_cvt_pk_bf16_f32 v223, v230, v231
	v_cvt_pk_bf16_f32 v224, v232, v233
	v_cvt_pk_bf16_f32 v225, v236, v237
	v_cvt_pk_bf16_f32 v226, v240, v241
	v_cvt_pk_bf16_f32 v227, v244, v245
	v_cvt_pk_bf16_f32 v228, v234, v235
	v_cvt_pk_bf16_f32 v229, v238, v239
	v_cvt_pk_bf16_f32 v230, v242, v243
	v_cvt_pk_bf16_f32 v231, v246, v247
	ds_read_b64_tr_b16 v[232:233], v208 offset:17408
	ds_read_b64_tr_b16 v[236:237], v208 offset:17440
	ds_read_b64_tr_b16 v[234:235], v208 offset:22016
	ds_read_b64_tr_b16 v[240:241], v208 offset:26624
	ds_read_b64_tr_b16 v[242:243], v208 offset:31232
	ds_read_b64_tr_b16 v[238:239], v208 offset:22048
	ds_read_b64_tr_b16 v[244:245], v208 offset:26656
	ds_read_b64_tr_b16 v[246:247], v208 offset:31264
	v_exp_f32_e64 v125, -v124
	v_mov_b32_e32 v116, v112
	v_mov_b32_e32 v117, v108
	v_mov_b32_e32 v108, v113
	v_mov_b32_e32 v112, v114
	v_mov_b32_e32 v113, v110
	v_mov_b32_e32 v110, v115
	v_pk_add_f32 v[108:109], v[116:117], v[108:109]
	v_pk_add_f32 v[110:111], v[112:113], v[110:111]
	v_mul_f32_e32 v136, v150, v125
	v_pk_add_f32 v[108:109], v[108:109], v[110:111]
	v_add_f32_e32 v3, v215, v124
	v_sub_f32_e32 v79, v47, v124
	v_sub_f32_e32 v78, v46, v124
	v_sub_f32_e32 v77, v45, v124
	v_sub_f32_e32 v76, v44, v124
	v_sub_f32_e32 v99, v51, v124
	v_sub_f32_e32 v98, v50, v124
	v_sub_f32_e32 v97, v49, v124
	v_sub_f32_e32 v96, v48, v124
	v_sub_f32_e32 v107, v55, v124
	v_sub_f32_e32 v106, v54, v124
	v_sub_f32_e32 v105, v53, v124
	v_sub_f32_e32 v104, v52, v124
	v_sub_f32_e32 v83, v59, v124
	v_sub_f32_e32 v82, v58, v124
	v_sub_f32_e32 v81, v57, v124
	v_sub_f32_e32 v80, v56, v124
	v_pk_fma_f32 v[158:159], v[156:157], v[136:137], v[108:109] op_sel_hi:[1,0,1]
	v_pk_mul_f32 v[110:111], v[66:67], v[136:137] op_sel_hi:[1,0]
	v_pk_mul_f32 v[108:109], v[64:65], v[136:137] op_sel_hi:[1,0]
	v_pk_mul_f32 v[114:115], v[74:75], v[136:137] op_sel_hi:[1,0]
	v_pk_mul_f32 v[112:113], v[72:73], v[136:137] op_sel_hi:[1,0]
	v_pk_mul_f32 v[118:119], v[62:63], v[136:137] op_sel_hi:[1,0]
	v_pk_mul_f32 v[116:117], v[60:61], v[136:137] op_sel_hi:[1,0]
	v_pk_mul_f32 v[122:123], v[70:71], v[136:137] op_sel_hi:[1,0]
	v_pk_mul_f32 v[120:121], v[68:69], v[136:137] op_sel_hi:[1,0]
	v_pk_mul_f32 v[126:127], v[90:91], v[136:137] op_sel_hi:[1,0]
	v_pk_mul_f32 v[124:125], v[88:89], v[136:137] op_sel_hi:[1,0]
	v_pk_mul_f32 v[130:131], v[102:103], v[136:137] op_sel_hi:[1,0]
	v_pk_mul_f32 v[128:129], v[100:101], v[136:137] op_sel_hi:[1,0]
	v_pk_mul_f32 v[134:135], v[86:87], v[136:137] op_sel_hi:[1,0]
	v_pk_mul_f32 v[132:133], v[84:85], v[136:137] op_sel_hi:[1,0]
	v_pk_mul_f32 v[138:139], v[94:95], v[136:137] op_sel_hi:[1,0]
	v_pk_mul_f32 v[136:137], v[92:93], v[136:137] op_sel_hi:[1,0]
	s_setprio 1
	s_waitcnt lgkmcnt(5)
; #define LAS __attribute__((address_space(3)))
; #define MFMA16(a, b, c) __builtin_amdgcn_mfma_f32_16x16x32_bf16((a), (b), (c), 0, 0, 0)
; DI u32x2 tr4(const LAS unsigned char* p) { return __builtin_bit_cast(u32x2, __builtin_amdgcn_ds_read_tr16_b64_v4i16((LAS v4i16_t*)p)); }
; DI void at_pv(AtState& S, const f32x4 (&s1)[4], const f32x4 (&s2)[4], float alpha, float ps1, float ps2, const LAS unsigned char* buf, int hh, int fq, int tq, int tp) {
;     ...
;     for (int dh = 0; dh < 2; ++dh) {
;         bf16x8 vt[2][2];
; #pragma unroll
;         for (int d2 = 0; d2 < 2; ++d2)
; #pragma unroll
;             for (int s = 0; s < 2; ++s) { const int dt = 2 * dh + d2; const LAS unsigned char* vr = buf + AT_V + (32 * s + 4 * fq + tq) * 288 + (hh * 64 + 16 * dt + 4 * tp) * 2; vt[d2][s] = cat44(tr4(vr), tr4(vr + 16 * 288)); }
;         __builtin_amdgcn_s_setprio(1);
; #pragma unroll
;         for (int s = 0; s < 2; ++s)
; #pragma unroll
;             for (int d2 = 0; d2 < 2; ++d2) { const int dt = 2 * dh + d2; S.O1[dt] = MFMA16(vt[d2][s], p1[s], S.O1[dt]); S.O2[dt] = MFMA16(vt[d2][s], p2[s], S.O2[dt]); }
;         __builtin_amdgcn_s_setprio(0);
;         __builtin_amdgcn_sched_barrier(0);
;     }
	v_mfma_f32_16x16x32_bf16 v[108:111], v[232:235], v[216:219], v[108:111]
	v_mfma_f32_16x16x32_bf16 v[112:115], v[232:235], v[220:223], v[112:115]
	s_waitcnt lgkmcnt(2)
	v_mfma_f32_16x16x32_bf16 v[232:235], v[236:239], v[216:219], v[116:119]
	v_mfma_f32_16x16x32_bf16 v[236:239], v[236:239], v[220:223], v[120:123]
	v_mfma_f32_16x16x32_bf16 v[120:123], v[240:243], v[224:227], v[108:111]
	v_mfma_f32_16x16x32_bf16 v[116:119], v[240:243], v[228:231], v[112:115]
	s_waitcnt lgkmcnt(0)
	v_mfma_f32_16x16x32_bf16 v[112:115], v[244:247], v[224:227], v[232:235]
	v_mfma_f32_16x16x32_bf16 v[108:111], v[244:247], v[228:231], v[236:239]
	s_setprio 0
	s_nop 0
	ds_read_b64_tr_b16 v[232:233], v208 offset:17472
	ds_read_b64_tr_b16 v[236:237], v208 offset:17504
	ds_read_b64_tr_b16 v[234:235], v208 offset:22080
	ds_read_b64_tr_b16 v[238:239], v208 offset:22112
	ds_read_b64_tr_b16 v[240:241], v208 offset:26688
	ds_read_b64_tr_b16 v[242:243], v208 offset:31296
	ds_read_b64_tr_b16 v[246:247], v208 offset:31328
	ds_read_b64_tr_b16 v[244:245], v208 offset:26720
	s_setprio 1
	s_waitcnt lgkmcnt(5)
	v_mfma_f32_16x16x32_bf16 v[124:127], v[232:235], v[216:219], v[124:127]
	v_mfma_f32_16x16x32_bf16 v[128:131], v[232:235], v[220:223], v[128:131]
	s_waitcnt lgkmcnt(4)
	v_mfma_f32_16x16x32_bf16 v[216:219], v[236:239], v[216:219], v[132:135]
	v_mfma_f32_16x16x32_bf16 v[220:223], v[236:239], v[220:223], v[136:139]
	s_waitcnt lgkmcnt(2)
	v_mfma_f32_16x16x32_bf16 v[136:139], v[240:243], v[224:227], v[124:127]
	v_mfma_f32_16x16x32_bf16 v[132:135], v[240:243], v[228:231], v[128:131]
	s_waitcnt lgkmcnt(0)
	v_mfma_f32_16x16x32_bf16 v[128:131], v[244:247], v[224:227], v[216:219]
	v_mfma_f32_16x16x32_bf16 v[124:127], v[244:247], v[228:231], v[220:223]
	s_setprio 0
	s_cbranch_execnz .LBB0_1380

; DI void lds_barrier() { asm volatile("s_waitcnt lgkmcnt(0)" ::: "memory"); __builtin_amdgcn_s_barrier(); asm volatile("" ::: "memory"); }
; template <int VAR>
; DI void attn_tile(AtState& S, const LAS unsigned char* buf, const bf16x8 q1, const bf16x8 q2, int kt, bool diag, int qpos0, int qpos_l, float slope2, float adv, float decay, int hh, int fr, int fq) {
;     ...
;         asm volatile("; attention: fast tile" ::: "memory");
;         at_qk(s1, s2, buf, q1, q2, S.cinit, hh, fr, fq);
;         S.ref += adv;
;         at_exp(s1, s2, ps1, ps2);
;         if (__any(!(ps1 + ps2 < 0x1p60f))) {
;             asm volatile("; attention: bump" ::: "memory");
;             at_qk(s1, s2, buf, q1, q2, S.cinit, hh, fr, fq);
;             float lm = -1e30f;
; #pragma unroll
;             for (int k4 = 0; k4 < 4; ++k4)
; #pragma unroll
;                 for (int j = 0; j < 4; ++j) lm = fmaxf(lm, fmaxf(s1[k4][j], s2[k4][j]));
;             lm = fmaxf(lm, __shfl_xor(lm, 16)); lm = fmaxf(lm, __shfl_xor(lm, 32));
; template <int VAR>
; DI void attn_segment(const Args& a, const Frame& F, int l, int qrow0, int qpos0, int hp, int ntile, int nf32, const float* ck, const float* cv, int prow0) {
;     ...
;             atb_commit(ra, F.lds + ((kt + 1) & 1) * AT_BUF, tid);
;             lds_barrier();
;             if (kt + 1 >= ntile) break;
;             atb_issue(ra, pb + (size_t)(kt + 3 < nl ? kt + 3 : nl) * TSTR, voff);
;             attn_tile<VAR>(S, F.lds + ((kt + 1) & 1) * AT_BUF, q1, q2, kt + 1, kt + 2 == ntile, qpos0, qpos_l, slope2, adv, decay, hh, fr, fq);
.Lcommit_done_A:
	s_waitcnt lgkmcnt(0)
	s_barrier
	s_add_i32 s14, s26, -2
	s_cmp_ge_i32 s14, s24
	s_mov_b64 s[14:15], -1
	s_cbranch_scc1 .LBB0_1375
	ds_read_b128 v[44:47], v213 offset:35840
	ds_read_b128 v[48:51], v213 offset:35904
	ds_read_b128 v[52:55], v213 offset:40192
	ds_read_b128 v[56:59], v213 offset:40256
	ds_read_b128 v[60:63], v213 offset:44544
	ds_read_b128 v[64:67], v213 offset:44608
	ds_read_b128 v[68:71], v213 offset:48896
	ds_read_b128 v[72:75], v213 offset:48960
	s_min_i32 s14, s26, s25
	s_ashr_i32 s15, s14, 31
	s_lshl_b64 s[14:15], s[14:15], 18
	s_add_u32 s14, s0, s14
	s_addc_u32 s15, s1, s15
	v_lshl_add_u64 v[16:17], s[14:15], 0, v[144:145]
	v_lshl_add_u64 v[24:25], s[14:15], 0, v[146:147]
	global_load_dwordx4 v[12:15], v[16:17], off offset:1024
	s_nop 0
	global_load_dwordx4 v[16:19], v[16:17], off offset:1536
	s_nop 0
	global_load_dwordx4 v[20:23], v[24:25], off offset:1024
	s_nop 0
	global_load_dwordx4 v[24:27], v[24:25], off offset:1536
	s_cmpk_lg_i32 s28, 0x41
	s_mov_b64 s[14:15], -1
	s_cbranch_scc0 .LBB0_1391
	s_waitcnt lgkmcnt(7)
	v_mfma_f32_16x16x32_bf16 v[44:47], v[44:47], v[4:7], v[76:79]
	v_add_f32_e32 v215, v205, v3
	s_waitcnt lgkmcnt(6)
	v_mfma_f32_16x16x32_bf16 v[48:51], v[48:51], v[8:11], v[76:79]
	s_waitcnt lgkmcnt(5)
	v_mfma_f32_16x16x32_bf16 v[52:55], v[52:55], v[4:7], v[96:99]
	s_nop 2
	v_exp_f32_e32 v164, v44
	v_exp_f32_e32 v165, v45
	v_exp_f32_e32 v168, v46
	s_waitcnt lgkmcnt(4)
	v_mfma_f32_16x16x32_bf16 v[56:59], v[56:59], v[8:11], v[96:99]
	v_exp_f32_e32 v169, v47
	v_exp_f32_e32 v162, v48
	v_exp_f32_e32 v163, v49
	s_waitcnt lgkmcnt(3)
	v_mfma_f32_16x16x32_bf16 v[60:63], v[60:63], v[4:7], v[104:107]
	v_exp_f32_e32 v166, v50
	v_exp_f32_e32 v167, v51
	v_exp_f32_e32 v172, v52
	s_waitcnt lgkmcnt(2)
	v_mfma_f32_16x16x32_bf16 v[44:47], v[64:67], v[8:11], v[104:107]
	v_exp_f32_e32 v170, v56
	v_exp_f32_e32 v173, v53
	v_exp_f32_e32 v176, v54
	s_waitcnt lgkmcnt(1)
	v_mfma_f32_16x16x32_bf16 v[48:51], v[68:71], v[4:7], v[80:83]
	v_exp_f32_e32 v177, v55
	v_exp_f32_e32 v174, v58
	v_exp_f32_e32 v175, v59
	s_waitcnt lgkmcnt(0)
	v_mfma_f32_16x16x32_bf16 v[64:67], v[72:75], v[8:11], v[80:83]
	v_exp_f32_e32 v171, v57
	v_exp_f32_e32 v180, v60
	v_exp_f32_e32 v178, v44
	v_exp_f32_e32 v181, v61
	v_exp_f32_e32 v179, v45
	v_exp_f32_e32 v184, v62
	v_exp_f32_e32 v185, v63
	v_exp_f32_e32 v182, v46
	v_exp_f32_e32 v183, v47
	v_exp_f32_e32 v188, v48
	v_exp_f32_e32 v186, v64
	v_exp_f32_e32 v189, v49
	v_exp_f32_e32 v192, v50
	v_exp_f32_e32 v193, v51
	v_exp_f32_e32 v190, v66
	v_exp_f32_e32 v191, v67
	v_exp_f32_e32 v187, v65
	v_pk_add_f32 v[52:53], v[168:169], v[176:177]
	v_pk_add_f32 v[54:55], v[164:165], v[172:173]
	v_pk_add_f32 v[56:57], v[166:167], v[174:175]
	v_pk_add_f32 v[58:59], v[162:163], v[170:171]
	v_pk_add_f32 v[44:45], v[54:55], v[180:181]
	v_pk_add_f32 v[46:47], v[52:53], v[184:185]
	v_pk_add_f32 v[52:53], v[58:59], v[178:179]
	v_pk_add_f32 v[54:55], v[56:57], v[182:183]
	v_pk_add_f32 v[46:47], v[46:47], v[192:193]
	v_pk_add_f32 v[44:45], v[44:45], v[188:189]
	v_pk_add_f32 v[48:49], v[54:55], v[190:191]
	v_pk_add_f32 v[50:51], v[52:53], v[186:187]
	v_mov_b32_e32 v53, v44
	v_mov_b32_e32 v52, v50
	v_mov_b32_e32 v44, v51
	v_mov_b32_e32 v50, v48
	v_mov_b32_e32 v51, v46
	v_mov_b32_e32 v46, v49
	v_pk_add_f32 v[44:45], v[52:53], v[44:45]
	v_pk_add_f32 v[46:47], v[50:51], v[46:47]
	s_nop 0
	v_pk_add_f32 v[194:195], v[44:45], v[46:47]
	s_nop 0
	v_add_f32_e32 v44, v195, v194
	v_cmp_ngt_f32_e32 vcc, s65, v44
	s_cbranch_vccz .LBB0_1395
	ds_read_b128 v[44:47], v213 offset:35840
	ds_read_b128 v[48:51], v213 offset:35904
	ds_read_b128 v[52:55], v213 offset:40192
	ds_read_b128 v[56:59], v213 offset:40256
	ds_read_b128 v[60:63], v213 offset:44544
	ds_read_b128 v[64:67], v213 offset:44608
	ds_read_b128 v[68:71], v213 offset:48896
	ds_read_b128 v[72:75], v213 offset:48960
	s_waitcnt lgkmcnt(7)
	v_mfma_f32_16x16x32_bf16 v[44:47], v[44:47], v[4:7], v[76:79]
	s_waitcnt lgkmcnt(6)
	v_mfma_f32_16x16x32_bf16 v[48:51], v[48:51], v[8:11], v[76:79]
	s_waitcnt lgkmcnt(5)
	v_mfma_f32_16x16x32_bf16 v[52:55], v[52:55], v[4:7], v[96:99]
	s_waitcnt lgkmcnt(4)
	v_mfma_f32_16x16x32_bf16 v[56:59], v[56:59], v[8:11], v[96:99]
	s_waitcnt lgkmcnt(3)
	v_mfma_f32_16x16x32_bf16 v[60:63], v[60:63], v[4:7], v[104:107]
	s_waitcnt lgkmcnt(2)
	v_mfma_f32_16x16x32_bf16 v[64:67], v[64:67], v[8:11], v[104:107]
	s_waitcnt lgkmcnt(1)
	v_mfma_f32_16x16x32_bf16 v[68:71], v[68:71], v[4:7], v[80:83]
	s_waitcnt lgkmcnt(0)
	v_mfma_f32_16x16x32_bf16 v[72:75], v[72:75], v[8:11], v[80:83]
	v_max3_f32 v84, v44, v48, s60
	v_max3_f32 v84, v84, v45, v49
	v_max3_f32 v84, v84, v46, v50
	v_max3_f32 v84, v84, v47, v51
	v_max3_f32 v84, v84, v52, v56
	v_max3_f32 v84, v84, v53, v57
	v_max3_f32 v84, v84, v54, v58
	v_max3_f32 v84, v84, v55, v59
	v_max3_f32 v84, v84, v60, v64
	v_max3_f32 v84, v84, v61, v65
	v_max3_f32 v84, v84, v62, v66
	v_max3_f32 v84, v84, v63, v67
	v_max3_f32 v84, v84, v68, v72
	v_max3_f32 v84, v84, v69, v73
	v_max3_f32 v84, v84, v70, v74
	v_max3_f32 v84, v84, v71, v75
	v_and_b32_e32 v86, 64, v198
	v_mov_b32_e32 v85, v84
	v_mov_b32_e32 v255, v84
	s_nop 1
	v_permlane16_swap_b32_e32 v85, v255
	s_waitcnt lgkmcnt(0)
	v_max_f32_e32 v84, v85, v255
	v_mov_b32_e32 v85, v84
	v_mov_b32_e32 v255, v84
	s_nop 1
	v_permlane32_swap_b32_e32 v85, v255
	s_waitcnt lgkmcnt(0)
; #define LAS __attribute__((address_space(3)))
; DI float fast_exp2(float x) { return __builtin_amdgcn_exp2f(x); }
; #define MFMA16(a, b, c) __builtin_amdgcn_mfma_f32_16x16x32_bf16((a), (b), (c), 0, 0, 0)
; DI u32x2 tr4(const LAS unsigned char* p) { return __builtin_bit_cast(u32x2, __builtin_amdgcn_ds_read_tr16_b64_v4i16((LAS v4i16_t*)p)); }
; DI bf16x8 packp(f32x4 a, f32x4 b) { return __builtin_bit_cast(bf16x8, pack8(a, b)); }
; DI void at_pv(AtState& S, const f32x4 (&s1)[4], const f32x4 (&s2)[4], float alpha, float ps1, float ps2, const LAS unsigned char* buf, int hh, int fq, int tq, int tp) {
;     S.l1 = S.l1 * alpha + ps1; S.l2 = S.l2 * alpha + ps2;
; #pragma unroll
;     for (int dt = 0; dt < 4; ++dt) { S.O1[dt] = S.O1[dt] * alpha; S.O2[dt] = S.O2[dt] * alpha; }
;     bf16x8 p1[2], p2[2];
; #pragma unroll
;     for (int s = 0; s < 2; ++s) { p1[s] = packp(s1[2 * s], s1[2 * s + 1]); p2[s] = packp(s2[2 * s], s2[2 * s + 1]); }
; #pragma unroll
;     for (int dh = 0; dh < 2; ++dh) {
;         bf16x8 vt[2][2];
; #pragma unroll
;         for (int d2 = 0; d2 < 2; ++d2)
; #pragma unroll
;             for (int s = 0; s < 2; ++s) { const int dt = 2 * dh + d2; const LAS unsigned char* vr = buf + AT_V + (32 * s + 4 * fq + tq) * 288 + (hh * 64 + 16 * dt + 4 * tp) * 2; vt[d2][s] = cat44(tr4(vr), tr4(vr + 16 * 288)); }
;         __builtin_amdgcn_s_setprio(1);
; #pragma unroll
;         for (int s = 0; s < 2; ++s)
; #pragma unroll
;             for (int d2 = 0; d2 < 2; ++d2) { const int dt = 2 * dh + d2; S.O1[dt] = MFMA16(vt[d2][s], p1[s], S.O1[dt]); S.O2[dt] = MFMA16(vt[d2][s], p2[s], S.O2[dt]); }
;         __builtin_amdgcn_s_setprio(0);
;         __builtin_amdgcn_sched_barrier(0);
;     }
; template <int VAR>
; DI void attn_tile(AtState& S, const LAS unsigned char* buf, const bf16x8 q1, const bf16x8 q2, int kt, bool diag, int qpos0, int qpos_l, float slope2, float adv, float decay, int hh, int fr, int fq) {
;     ...
;             const float bump = fmaxf(lm, 0.f);
;             const float alpha = decay * fast_exp2(-bump); S.ref += bump;
; #pragma unroll
;             for (int k4 = 0; k4 < 4; ++k4) { s1[k4] = s1[k4] - bump; s2[k4] = s2[k4] - bump; S.cinit[k4] = S.cinit[k4] - bump; }
;             at_exp(s1, s2, ps1, ps2);
;             at_pv(S, s1, s2, alpha, ps1, ps2, buf, hh, fq, tq, tp);
	v_max3_f32 v84, v255, v85, 0
	v_sub_f32_e32 v86, v47, v84
	v_sub_f32_e32 v87, v46, v84
	v_sub_f32_e32 v88, v45, v84
	v_sub_f32_e32 v89, v44, v84
	v_sub_f32_e32 v90, v51, v84
	v_sub_f32_e32 v91, v50, v84
	v_sub_f32_e32 v92, v49, v84
	v_sub_f32_e32 v93, v48, v84
	v_sub_f32_e32 v94, v55, v84
	v_sub_f32_e32 v95, v54, v84
	v_sub_f32_e32 v101, v53, v84
	v_sub_f32_e32 v102, v52, v84
	v_sub_f32_e32 v103, v59, v84
	v_sub_f32_e32 v151, v58, v84
	v_sub_f32_e32 v156, v57, v84
	v_sub_f32_e32 v157, v56, v84
	v_exp_f32_e32 v216, v89
	v_exp_f32_e32 v220, v93
	v_exp_f32_e32 v217, v88
	v_exp_f32_e32 v221, v92
	v_exp_f32_e32 v218, v87
	v_exp_f32_e32 v222, v91
	v_exp_f32_e32 v219, v86
	v_exp_f32_e32 v223, v90
	v_sub_f32_e32 v237, v63, v84
	v_sub_f32_e32 v236, v62, v84
	v_sub_f32_e32 v233, v61, v84
	v_sub_f32_e32 v232, v60, v84
	v_sub_f32_e32 v239, v67, v84
	v_sub_f32_e32 v238, v66, v84
	v_sub_f32_e32 v235, v65, v84
	v_sub_f32_e32 v234, v64, v84
	v_exp_f32_e32 v224, v102
	v_exp_f32_e32 v226, v157
	v_exp_f32_e32 v225, v101
	v_exp_f32_e32 v227, v156
	v_exp_f32_e32 v228, v95
	v_exp_f32_e32 v230, v151
	v_exp_f32_e32 v229, v94
	v_exp_f32_e32 v231, v103
	v_sub_f32_e32 v71, v71, v84
	v_sub_f32_e32 v70, v70, v84
	v_sub_f32_e32 v69, v69, v84
	v_sub_f32_e32 v68, v68, v84
	v_sub_f32_e32 v75, v75, v84
	v_sub_f32_e32 v74, v74, v84
	v_sub_f32_e32 v73, v73, v84
	v_sub_f32_e32 v72, v72, v84
	v_exp_f32_e32 v232, v232
	v_exp_f32_e32 v234, v234
	v_exp_f32_e32 v233, v233
	v_exp_f32_e32 v235, v235
	v_exp_f32_e32 v236, v236
	v_exp_f32_e32 v238, v238
	v_exp_f32_e32 v237, v237
	v_exp_f32_e32 v239, v239
	v_exp_f32_e32 v240, v68
	v_exp_f32_e32 v242, v72
	v_exp_f32_e32 v241, v69
	v_exp_f32_e32 v243, v73
	v_exp_f32_e32 v244, v70
	v_exp_f32_e32 v246, v74
	v_exp_f32_e32 v245, v71
	v_exp_f32_e32 v247, v75
	v_pk_add_f32 v[62:63], v[228:229], v[218:219]
	v_pk_add_f32 v[60:61], v[224:225], v[216:217]
	v_pk_add_f32 v[66:67], v[230:231], v[222:223]
	v_pk_add_f32 v[64:65], v[226:227], v[220:221]
	v_pk_add_f32 v[60:61], v[232:233], v[60:61]
	v_pk_add_f32 v[62:63], v[236:237], v[62:63]
	v_pk_add_f32 v[64:65], v[234:235], v[64:65]
	v_pk_add_f32 v[66:67], v[238:239], v[66:67]
	v_pk_add_f32 v[62:63], v[244:245], v[62:63]
	v_pk_add_f32 v[60:61], v[240:241], v[60:61]
	v_pk_add_f32 v[66:67], v[246:247], v[66:67]
	v_pk_add_f32 v[64:65], v[242:243], v[64:65]
	v_cvt_pk_bf16_f32 v216, v216, v217
	v_cvt_pk_bf16_f32 v217, v218, v219
	v_cvt_pk_bf16_f32 v218, v224, v225
	v_cvt_pk_bf16_f32 v219, v228, v229
	v_cvt_pk_bf16_f32 v220, v220, v221
	v_cvt_pk_bf16_f32 v221, v222, v223
	v_cvt_pk_bf16_f32 v222, v226, v227
	v_cvt_pk_bf16_f32 v223, v230, v231
	v_cvt_pk_bf16_f32 v224, v232, v233
	v_cvt_pk_bf16_f32 v225, v236, v237
	v_cvt_pk_bf16_f32 v226, v240, v241
	v_cvt_pk_bf16_f32 v227, v244, v245
	v_cvt_pk_bf16_f32 v228, v234, v235
	v_cvt_pk_bf16_f32 v229, v238, v239
	v_cvt_pk_bf16_f32 v230, v242, v243
	v_cvt_pk_bf16_f32 v231, v246, v247
	ds_read_b64_tr_b16 v[232:233], v208 offset:53248
	ds_read_b64_tr_b16 v[236:237], v208 offset:53280
	ds_read_b64_tr_b16 v[234:235], v208 offset:57856
	ds_read_b64_tr_b16 v[240:241], v208 offset:62464
	ds_read_b64_tr_b16 v[242:243], v209 offset:4608
	ds_read_b64_tr_b16 v[238:239], v208 offset:57888
	ds_read_b64_tr_b16 v[244:245], v208 offset:62496
	ds_read_b64_tr_b16 v[246:247], v210 offset:4608
	v_exp_f32_e64 v85, -v84
	v_mov_b32_e32 v68, v64
	v_mov_b32_e32 v69, v60
	v_mov_b32_e32 v60, v65
	v_mov_b32_e32 v64, v66
	v_mov_b32_e32 v65, v62
	v_mov_b32_e32 v62, v67
	v_pk_add_f32 v[60:61], v[68:69], v[60:61]
	v_pk_add_f32 v[62:63], v[64:65], v[62:63]
	v_mul_f32_e32 v100, v150, v85
	v_pk_add_f32 v[60:61], v[60:61], v[62:63]
	v_add_f32_e32 v214, v215, v84
	v_sub_f32_e32 v47, v79, v84
	v_sub_f32_e32 v46, v78, v84
	v_sub_f32_e32 v45, v77, v84
	v_sub_f32_e32 v44, v76, v84
	v_sub_f32_e32 v51, v99, v84
	v_sub_f32_e32 v50, v98, v84
	v_sub_f32_e32 v49, v97, v84
	v_sub_f32_e32 v48, v96, v84
	v_sub_f32_e32 v55, v107, v84
	v_sub_f32_e32 v54, v106, v84
	v_sub_f32_e32 v53, v105, v84
	v_sub_f32_e32 v52, v104, v84
	v_sub_f32_e32 v59, v83, v84
	v_sub_f32_e32 v58, v82, v84
	v_sub_f32_e32 v57, v81, v84
	v_sub_f32_e32 v56, v80, v84
	v_pk_fma_f32 v[156:157], v[158:159], v[100:101], v[60:61] op_sel_hi:[1,0,1]
	v_pk_mul_f32 v[62:63], v[122:123], v[100:101] op_sel_hi:[1,0]
	v_pk_mul_f32 v[60:61], v[120:121], v[100:101] op_sel_hi:[1,0]
	v_pk_mul_f32 v[66:67], v[118:119], v[100:101] op_sel_hi:[1,0]
	v_pk_mul_f32 v[64:65], v[116:117], v[100:101] op_sel_hi:[1,0]
	v_pk_mul_f32 v[70:71], v[114:115], v[100:101] op_sel_hi:[1,0]
	v_pk_mul_f32 v[68:69], v[112:113], v[100:101] op_sel_hi:[1,0]
	v_pk_mul_f32 v[74:75], v[110:111], v[100:101] op_sel_hi:[1,0]
	v_pk_mul_f32 v[72:73], v[108:109], v[100:101] op_sel_hi:[1,0]
	v_pk_mul_f32 v[86:87], v[138:139], v[100:101] op_sel_hi:[1,0]
	v_pk_mul_f32 v[84:85], v[136:137], v[100:101] op_sel_hi:[1,0]
	v_pk_mul_f32 v[90:91], v[134:135], v[100:101] op_sel_hi:[1,0]
	v_pk_mul_f32 v[88:89], v[132:133], v[100:101] op_sel_hi:[1,0]
	v_pk_mul_f32 v[94:95], v[130:131], v[100:101] op_sel_hi:[1,0]
	v_pk_mul_f32 v[92:93], v[128:129], v[100:101] op_sel_hi:[1,0]
	v_pk_mul_f32 v[102:103], v[126:127], v[100:101] op_sel_hi:[1,0]
	v_pk_mul_f32 v[100:101], v[124:125], v[100:101] op_sel_hi:[1,0]
	s_setprio 1
	s_waitcnt lgkmcnt(5)
	v_mfma_f32_16x16x32_bf16 v[60:63], v[232:235], v[216:219], v[60:63]
	v_mfma_f32_16x16x32_bf16 v[232:235], v[232:235], v[220:223], v[64:67]
	s_waitcnt lgkmcnt(2)
	v_mfma_f32_16x16x32_bf16 v[68:71], v[236:239], v[216:219], v[68:71]
	v_mfma_f32_16x16x32_bf16 v[236:239], v[236:239], v[220:223], v[72:75]
	v_mfma_f32_16x16x32_bf16 v[64:67], v[240:243], v[224:227], v[60:63]
	v_mfma_f32_16x16x32_bf16 v[72:75], v[240:243], v[228:231], v[232:235]
	s_waitcnt lgkmcnt(0)
	v_mfma_f32_16x16x32_bf16 v[60:63], v[244:247], v[224:227], v[68:71]
	v_mfma_f32_16x16x32_bf16 v[68:71], v[244:247], v[228:231], v[236:239]
	s_setprio 0
	ds_read_b64_tr_b16 v[232:233], v208 offset:53312
	s_nop 0
	ds_read_b64_tr_b16 v[236:237], v208 offset:53344
	ds_read_b64_tr_b16 v[234:235], v208 offset:57920
	ds_read_b64_tr_b16 v[238:239], v208 offset:57952
	ds_read_b64_tr_b16 v[240:241], v208 offset:62528
	ds_read_b64_tr_b16 v[242:243], v211 offset:4608
	ds_read_b64_tr_b16 v[246:247], v212 offset:4608
	ds_read_b64_tr_b16 v[244:245], v208 offset:62560
	s_setprio 1
	s_waitcnt lgkmcnt(5)
	v_mfma_f32_16x16x32_bf16 v[84:87], v[232:235], v[216:219], v[84:87]
	v_mfma_f32_16x16x32_bf16 v[232:235], v[232:235], v[220:223], v[88:91]
	s_waitcnt lgkmcnt(4)
	v_mfma_f32_16x16x32_bf16 v[92:95], v[236:239], v[216:219], v[92:95]
	v_mfma_f32_16x16x32_bf16 v[216:219], v[236:239], v[220:223], v[100:103]
	s_waitcnt lgkmcnt(2)
	v_mfma_f32_16x16x32_bf16 v[88:91], v[240:243], v[224:227], v[84:87]
	v_mfma_f32_16x16x32_bf16 v[100:103], v[240:243], v[228:231], v[232:235]
	s_waitcnt lgkmcnt(0)
	v_mfma_f32_16x16x32_bf16 v[84:87], v[244:247], v[224:227], v[92:95]
	v_mfma_f32_16x16x32_bf16 v[92:95], v[244:247], v[228:231], v[216:219]
	s_setprio 0
	s_cbranch_execnz .LBB0_1390
